# adds: layer-0 work queue issues its last 8 conv items as 16 half items (32 tokens) to shorten the queue tail
# speedup vs baseline: 1.0296x; 1.0029x over previous
.LBB0_361:
	v_writelane_b32 v242, s10, 48
	s_and_b64 s[0:1], s[10:11], exec
	s_cselect_b32 s87, 0, 4
	s_lshl_b32 s92, s96, 1
	s_xor_b32 s91, s87, 0x104
	s_lshl_b64 s[0:1], s[92:93], 2
	v_readlane_b32 s4, v243, 24
	s_add_u32 s46, s4, s0
	v_readlane_b32 s0, v243, 25
	s_addc_u32 s47, s0, s1
	s_lshl_b32 s0, s87, 1
	v_writelane_b32 v242, s11, 49
	s_addk_i32 s0, 0xfefc
	v_writelane_b32 v242, s0, 51
	s_mul_i32 s92, s96, 0x3e00
	v_readlane_b32 s4, v242, 32
	s_lshl_b32 s97, s91, 1
	s_cmp_eq_u32 s87, 0
	s_cselect_b32 s98, 8, 0
	s_add_i32 s97, s97, s98
	s_lshl_b64 s[0:1], s[92:93], 2
	v_readlane_b32 s6, v242, 34
	v_readlane_b32 s7, v242, 35
	s_add_u32 s50, s6, s0
	v_readlane_b32 s5, v242, 33
	s_addc_u32 s51, s7, s1
	s_lshl_b32 s52, s96, 9
	s_mov_b32 s53, s93
	v_readlane_b32 s10, v242, 38
	s_lshl_b64 s[4:5], s[52:53], 2
	v_readlane_b32 s11, v242, 39
	s_add_u32 s54, s10, s4
	s_addc_u32 s55, s11, s5
	v_readlane_b32 s12, v242, 26
	v_readlane_b32 s13, v242, 27
	s_add_u32 s58, s12, s4
	v_readlane_b32 s14, v242, 28
	s_addc_u32 s59, s13, s5
	s_lshl_b32 s53, s96, 3
	v_readlane_b32 s15, v242, 29
	s_add_u32 s0, s14, s4
	s_addc_u32 s1, s15, s5
	v_readlane_b32 s6, v242, 24
	v_readlane_b32 s7, v242, 25
	s_add_u32 s72, s6, s4
	s_addc_u32 s73, s7, s5
	v_readlane_b32 s8, v242, 36
	v_readlane_b32 s9, v242, 37
	s_branch .LBB0_364

.LBB0_368:
	s_or_b64 exec, exec, s[40:41]
	v_mov_b32_e32 v0, s33
	s_waitcnt lgkmcnt(0)
	s_barrier
	ds_read_b32 v0, v0
	s_waitcnt lgkmcnt(0)
	v_cmp_le_i32_e64 s[40:41], s97, v0
	v_readfirstlane_b32 s92, v0
	s_and_b64 vcc, exec, s[40:41]
	s_cbranch_vccnz .LBB0_363
	s_cmp_ge_i32 s92, s91
	s_mov_b64 s[42:43], -1
	s_cbranch_scc0 .LBB0_397
	v_mov_b32_e32 v108, v175
	s_movk_i32 s5, 0x3000
	v_ashrrev_i32_e32 v109, 31, v108
	v_lshl_add_u64 v[0:1], v[108:109], 2, s[50:51]
	v_add_co_u32_e32 v2, vcc, s74, v0
	s_mov_b64 s[44:45], s[68:69]
	s_nop 0
	v_addc_co_u32_e32 v3, vcc, 0, v1, vcc
	v_add_co_u32_e32 v4, vcc, s3, v0
	v_readlane_b32 s4, v242, 51
	s_nop 0
	v_addc_co_u32_e32 v5, vcc, 0, v1, vcc
	v_add_co_u32_e32 v6, vcc, s5, v0
	s_movk_i32 s5, 0x4000
	s_nop 0
	v_addc_co_u32_e32 v7, vcc, 0, v1, vcc
	v_add_co_u32_e32 v8, vcc, s5, v0
	s_movk_i32 s5, 0x5000
	s_nop 0
	v_addc_co_u32_e32 v9, vcc, 0, v1, vcc
	v_add_co_u32_e32 v10, vcc, s5, v0
	s_movk_i32 s5, 0x6000
	s_nop 0
	v_addc_co_u32_e32 v11, vcc, 0, v1, vcc
	v_add_co_u32_e32 v12, vcc, s5, v0
	s_movk_i32 s5, 0x7000
	s_nop 0
	v_addc_co_u32_e32 v13, vcc, 0, v1, vcc
	global_load_dword v109, v[4:5], off offset:-4096
	global_load_dword v110, v[4:5], off
	global_load_dword v111, v[4:5], off offset:2048
	global_load_dword v112, v[8:9], off offset:-4096
	global_load_dword v113, v[8:9], off
	global_load_dword v114, v[8:9], off offset:2048
	global_load_dword v115, v[12:13], off offset:-4096
	global_load_dword v116, v[12:13], off
	v_add_co_u32_e32 v4, vcc, s5, v0
	s_mov_b32 s5, 0x8000
	s_nop 0
	v_addc_co_u32_e32 v5, vcc, 0, v1, vcc
	v_add_co_u32_e32 v8, vcc, s5, v0
	s_mov_b32 s5, 0x9000
	s_nop 0
	v_addc_co_u32_e32 v9, vcc, 0, v1, vcc
	v_add_co_u32_e32 v14, vcc, s5, v0
	s_mov_b32 s5, 0xa000
	s_nop 0
	v_addc_co_u32_e32 v15, vcc, 0, v1, vcc
	v_add_co_u32_e32 v16, vcc, s5, v0
	s_mov_b32 s5, 0xb000
	s_nop 0
	v_addc_co_u32_e32 v17, vcc, 0, v1, vcc
	v_add_co_u32_e32 v18, vcc, s5, v0
	s_mov_b32 s5, 0xc000
	s_nop 0
	v_addc_co_u32_e32 v19, vcc, 0, v1, vcc
	v_add_co_u32_e32 v20, vcc, s5, v0
	s_mov_b32 s5, 0xd000
	s_nop 0
	v_addc_co_u32_e32 v21, vcc, 0, v1, vcc
	global_load_dword v117, v[12:13], off offset:2048
	global_load_dword v118, v[8:9], off offset:-4096
	global_load_dword v119, v[8:9], off
	global_load_dword v120, v[8:9], off offset:2048
	global_load_dword v121, v[16:17], off offset:-4096
	global_load_dword v122, v[16:17], off
	global_load_dword v123, v[16:17], off offset:2048
	global_load_dword v124, v[20:21], off offset:-4096
	global_load_dword v125, v[0:1], off
	global_load_dword v126, v[0:1], off offset:2048
	global_load_dword v127, v[2:3], off offset:2048
	global_load_dword v128, v[6:7], off offset:2048
	global_load_dword v129, v[10:11], off offset:2048
	global_load_dword v130, v[4:5], off offset:2048
	global_load_dword v131, v[14:15], off offset:2048
	global_load_dword v132, v[18:19], off offset:2048
	v_add_co_u32_e32 v2, vcc, s5, v0
	s_mov_b32 s5, 0xe000
	s_nop 0
	v_addc_co_u32_e32 v3, vcc, 0, v1, vcc
	s_add_i32 s4, s4, s92
	v_add_co_u32_e32 v4, vcc, s5, v0
	s_add_u32 s48, s44, 0x7900000
	s_nop 0
	v_addc_co_u32_e32 v5, vcc, 0, v1, vcc
	s_mov_b32 s5, 0xf000
	s_addc_u32 s49, s45, 0
	s_lshl_b32 s82, s4, 6
	s_cmpk_ge_i32 s4, 0xfc
	s_cselect_b32 s98, 1, 0
	s_cmp_eq_u32 s87, 0
	s_cselect_b32 s99, 1, 0
	s_and_b32 s98, s98, s99
	s_add_i32 s99, s4, 0xfc
	s_lshl_b32 s99, s99, 5
	s_cmp_lg_u32 s98, 0
	s_cselect_b32 s82, s99, s82
	v_add_co_u32_e32 v0, vcc, s5, v0
	s_cmp_lt_i32 s4, 4
	global_load_dword v133, v[20:21], off
	global_load_dword v134, v[20:21], off offset:2048
	global_load_dword v135, v[4:5], off offset:-4096
	global_load_dword v136, v[4:5], off
	global_load_dword v137, v[4:5], off offset:2048
	v_addc_co_u32_e32 v1, vcc, 0, v1, vcc
	global_load_dword v138, v[2:3], off offset:2048
	global_load_dword v139, v[0:1], off
	v_add_u32_e32 v0, s52, v108
	v_readlane_b32 s8, v242, 32
	v_ashrrev_i32_e32 v142, 6, v108
	s_cselect_b32 s4, 0, 0x100
	v_ashrrev_i32_e32 v1, 31, v0
	v_readlane_b32 s12, v242, 36
	v_readlane_b32 s13, v242, 37
	s_cselect_b32 s5, 0x100, s31
	s_add_i32 s6, s82, -15
	v_min_i32_e32 v16, 0x5d, v142
	v_lshl_add_u64 v[0:1], v[0:1], 2, s[12:13]
	s_add_i32 s7, s5, -1
	v_add_u32_e32 v16, s6, v16
	global_load_dword v140, v[0:1], off
	v_lshlrev_b32_e32 v0, 3, v108
	v_min_i32_e32 v17, s7, v16
	v_mov_b32_e32 v20, s4
	v_cmp_gt_i32_e32 vcc, s4, v16
	v_readlane_b32 s9, v242, 33
	v_and_b32_e32 v141, 0x1f8, v0
	v_cndmask_b32_e32 v18, v17, v20, vcc
	v_mov_b64_e32 v[16:17], s[48:49]
	v_mad_u64_u32 v[18:19], s[8:9], v18, s62, v[16:17]
	v_lshlrev_b32_e32 v144, 1, v141
	v_lshl_add_u64 v[18:19], v[18:19], 0, v[144:145]
	v_add_co_u32_e32 v18, vcc, s74, v18
	v_lshlrev_b32_e32 v12, 2, v141
	s_nop 0
	v_addc_co_u32_e32 v19, vcc, 0, v19, vcc
	global_load_dwordx4 v[0:3], v12, s[54:55] offset:16
	global_load_dwordx4 v[4:7], v12, s[54:55]
	global_load_dwordx4 v[8:11], v12, s[58:59] offset:16
	s_nop 0
	global_load_dwordx4 v[12:15], v12, s[58:59]
	s_barrier
	global_load_dwordx4 v[104:107], v[18:19], off
	global_load_dwordx4 v[168:171], v[18:19], off offset:1024
	v_add_u32_e32 v18, 0x200, v108
	v_ashrrev_i32_e32 v166, 6, v18
	v_min_i32_e32 v18, 0x5d, v166
	v_add_u32_e32 v18, s6, v18
	v_min_i32_e32 v19, s7, v18
	v_cmp_gt_i32_e32 vcc, s4, v18
	v_readlane_b32 s10, v242, 34
	v_readlane_b32 s11, v242, 35
	v_cndmask_b32_e32 v18, v19, v20, vcc
	v_mad_u64_u32 v[18:19], s[8:9], v18, s62, v[16:17]
	v_lshl_add_u64 v[18:19], v[18:19], 0, v[144:145]
	v_add_co_u32_e32 v18, vcc, s74, v18
	v_readlane_b32 s14, v242, 38
	s_nop 0
	v_addc_co_u32_e32 v19, vcc, 0, v19, vcc
	global_load_dwordx4 v[96:99], v[18:19], off
	global_load_dwordx4 v[100:103], v[18:19], off offset:1024
	v_add_u32_e32 v18, 0x400, v108
	v_ashrrev_i32_e32 v165, 6, v18
	v_min_i32_e32 v18, 0x5d, v165
	v_add_u32_e32 v18, s6, v18
	v_min_i32_e32 v19, s7, v18
	v_cmp_gt_i32_e32 vcc, s4, v18
	v_readlane_b32 s15, v242, 39
	s_waitcnt vmcnt(3)
	v_lshlrev_b32_e32 v172, 16, v104
	v_cndmask_b32_e32 v18, v19, v20, vcc
	v_mad_u64_u32 v[18:19], s[8:9], v18, s62, v[16:17]
	v_lshl_add_u64 v[18:19], v[18:19], 0, v[144:145]
	v_add_co_u32_e32 v18, vcc, s74, v18
	s_waitcnt vmcnt(2)
	v_lshlrev_b32_e32 v156, 16, v168
	v_addc_co_u32_e32 v19, vcc, 0, v19, vcc
	global_load_dwordx4 v[88:91], v[18:19], off
	global_load_dwordx4 v[92:95], v[18:19], off offset:1024
	v_add_u32_e32 v18, 0x600, v108
	v_ashrrev_i32_e32 v164, 6, v18
	v_min_i32_e32 v18, 0x5d, v164
	v_add_u32_e32 v18, s6, v18
	v_min_i32_e32 v19, s7, v18
	v_cmp_gt_i32_e32 vcc, s4, v18
	v_mul_f32_e32 v156, 0xbfb8aa3b, v156
	v_exp_f32_e32 v167, v156
	v_cndmask_b32_e32 v18, v19, v20, vcc
	v_mad_u64_u32 v[18:19], s[8:9], v18, s62, v[16:17]
	v_lshl_add_u64 v[18:19], v[18:19], 0, v[144:145]
	v_add_co_u32_e32 v18, vcc, s74, v18
	v_and_b32_e32 v156, 0xffff0000, v168
	s_nop 0
	v_addc_co_u32_e32 v19, vcc, 0, v19, vcc
	global_load_dwordx4 v[80:83], v[18:19], off
	global_load_dwordx4 v[84:87], v[18:19], off offset:1024
	v_add_u32_e32 v18, 0x800, v108
	v_ashrrev_i32_e32 v163, 6, v18
	v_min_i32_e32 v18, 0x5d, v163
	v_add_u32_e32 v18, s6, v18
	v_min_i32_e32 v19, s7, v18
	v_cmp_gt_i32_e32 vcc, s4, v18
	v_mul_f32_e32 v156, 0xbfb8aa3b, v156
	v_exp_f32_e32 v168, v156
	v_cndmask_b32_e32 v18, v19, v20, vcc
	v_mad_u64_u32 v[18:19], s[8:9], v18, s62, v[16:17]
	v_lshl_add_u64 v[18:19], v[18:19], 0, v[144:145]
	v_add_co_u32_e32 v18, vcc, s74, v18
	v_add_f32_e32 v168, 1.0, v168
	s_nop 0
	v_addc_co_u32_e32 v19, vcc, 0, v19, vcc
	global_load_dwordx4 v[72:75], v[18:19], off
	global_load_dwordx4 v[76:79], v[18:19], off offset:1024
	v_add_u32_e32 v18, 0xa00, v108
	v_ashrrev_i32_e32 v162, 6, v18
	v_min_i32_e32 v18, 0x5d, v162
	v_add_u32_e32 v18, s6, v18
	v_min_i32_e32 v19, s7, v18
	v_cmp_gt_i32_e32 vcc, s4, v18
	v_rcp_f32_e32 v168, v168
	v_and_b32_e32 v104, 0xffff0000, v104
	v_cndmask_b32_e32 v18, v19, v20, vcc
	v_mad_u64_u32 v[18:19], s[8:9], v18, s62, v[16:17]
	v_lshl_add_u64 v[18:19], v[18:19], 0, v[144:145]
	v_add_co_u32_e32 v18, vcc, s74, v18
	v_add_f32_e32 v167, 1.0, v167
	s_nop 0
	v_addc_co_u32_e32 v19, vcc, 0, v19, vcc
	global_load_dwordx4 v[64:67], v[18:19], off
	global_load_dwordx4 v[68:71], v[18:19], off offset:1024
	v_add_u32_e32 v18, 0xc00, v108
	v_ashrrev_i32_e32 v161, 6, v18
	v_min_i32_e32 v18, 0x5d, v161
	v_add_u32_e32 v18, s6, v18
	v_min_i32_e32 v19, s7, v18
	v_cmp_gt_i32_e32 vcc, s4, v18
	v_mul_f32_e32 v104, v168, v104
	v_lshlrev_b32_e32 v168, 16, v169
	v_cndmask_b32_e32 v18, v19, v20, vcc
	v_mad_u64_u32 v[18:19], s[8:9], v18, s62, v[16:17]
	v_lshl_add_u64 v[18:19], v[18:19], 0, v[144:145]
	v_add_co_u32_e32 v18, vcc, s74, v18
	v_and_b32_e32 v169, 0xffff0000, v169
	s_nop 0
	v_addc_co_u32_e32 v19, vcc, 0, v19, vcc
	global_load_dwordx4 v[56:59], v[18:19], off
	global_load_dwordx4 v[60:63], v[18:19], off offset:1024
	v_add_u32_e32 v18, 0xe00, v108
	v_ashrrev_i32_e32 v160, 6, v18
	v_min_i32_e32 v18, 0x5d, v160
	v_add_u32_e32 v18, s6, v18
	v_min_i32_e32 v19, s7, v18
	v_cmp_gt_i32_e32 vcc, s4, v18
	v_rcp_f32_e32 v167, v167
	v_mul_f32_e32 v168, 0xbfb8aa3b, v168
	v_cndmask_b32_e32 v18, v19, v20, vcc
	v_mad_u64_u32 v[18:19], s[8:9], v18, s62, v[16:17]
	v_lshl_add_u64 v[18:19], v[18:19], 0, v[144:145]
	v_add_co_u32_e32 v18, vcc, s74, v18
	v_mul_f32_e32 v169, 0xbfb8aa3b, v169
	s_nop 0
	v_addc_co_u32_e32 v19, vcc, 0, v19, vcc
	global_load_dwordx4 v[48:51], v[18:19], off
	global_load_dwordx4 v[52:55], v[18:19], off offset:1024
	v_add_u32_e32 v18, 0x1000, v108
	v_ashrrev_i32_e32 v159, 6, v18
	v_min_i32_e32 v18, 0x5d, v159
	v_add_u32_e32 v18, s6, v18
	v_min_i32_e32 v19, s7, v18
	v_cmp_gt_i32_e32 vcc, s4, v18
	v_exp_f32_e32 v168, v168
	v_exp_f32_e32 v169, v169
	v_cndmask_b32_e32 v18, v19, v20, vcc
	v_mad_u64_u32 v[18:19], s[8:9], v18, s62, v[16:17]
	v_lshl_add_u64 v[18:19], v[18:19], 0, v[144:145]
	v_add_co_u32_e32 v18, vcc, s74, v18
	v_mul_f32_e32 v167, v167, v172
	s_nop 0
	v_addc_co_u32_e32 v19, vcc, 0, v19, vcc
	global_load_dwordx4 v[40:43], v[18:19], off
	global_load_dwordx4 v[44:47], v[18:19], off offset:1024
	v_add_u32_e32 v18, 0x1200, v108
	v_ashrrev_i32_e32 v158, 6, v18
	v_min_i32_e32 v18, 0x5d, v158
	v_add_u32_e32 v18, s6, v18
	v_min_i32_e32 v19, s7, v18
	v_cmp_gt_i32_e32 vcc, s4, v18
	v_add_u32_e32 v156, 0, v144
	s_nop 0
	v_cndmask_b32_e32 v18, v19, v20, vcc
	v_mad_u64_u32 v[18:19], s[8:9], v18, s62, v[16:17]
	v_lshl_add_u64 v[18:19], v[18:19], 0, v[144:145]
	v_add_co_u32_e32 v18, vcc, s74, v18
	s_nop 1
	v_addc_co_u32_e32 v19, vcc, 0, v19, vcc
	global_load_dwordx4 v[32:35], v[18:19], off
	global_load_dwordx4 v[36:39], v[18:19], off offset:1024
	v_add_u32_e32 v18, 0x1400, v108
	v_ashrrev_i32_e32 v157, 6, v18
	v_min_i32_e32 v18, 0x5d, v157
	v_add_u32_e32 v18, s6, v18
	v_min_i32_e32 v19, s7, v18
	v_cmp_gt_i32_e32 vcc, s4, v18
	s_nop 1
	v_cndmask_b32_e32 v18, v19, v20, vcc
	v_mad_u64_u32 v[18:19], s[8:9], v18, s62, v[16:17]
	v_lshl_add_u64 v[18:19], v[18:19], 0, v[144:145]
	v_add_co_u32_e32 v18, vcc, s74, v18
	s_nop 1
	v_addc_co_u32_e32 v19, vcc, 0, v19, vcc
	global_load_dwordx4 v[24:27], v[18:19], off
	global_load_dwordx4 v[28:31], v[18:19], off offset:1024
	v_add_u32_e32 v18, 0x1600, v108
	v_ashrrev_i32_e32 v143, 6, v18
	v_min_i32_e32 v18, 0x5d, v143
	v_add_u32_e32 v18, s6, v18
	v_min_i32_e32 v19, s7, v18
	v_cmp_gt_i32_e32 vcc, s4, v18
	s_nop 1
	v_cndmask_b32_e32 v18, v19, v20, vcc
	v_mad_u64_u32 v[16:17], s[8:9], v18, s62, v[16:17]
	v_lshl_add_u64 v[16:17], v[16:17], 0, v[144:145]
	v_add_co_u32_e32 v20, vcc, s74, v16
	s_nop 1
	v_addc_co_u32_e32 v21, vcc, 0, v17, vcc
	global_load_dwordx4 v[16:19], v[20:21], off
	s_nop 0
	global_load_dwordx4 v[20:23], v[20:21], off offset:1024
	v_cvt_pk_bf16_f32 v104, v167, v104
	v_add_f32_e32 v167, 1.0, v168
	v_add_f32_e32 v168, 1.0, v169
	v_rcp_f32_e32 v167, v167
	v_rcp_f32_e32 v168, v168
	v_lshlrev_b32_e32 v169, 16, v105
	v_and_b32_e32 v105, 0xffff0000, v105
	v_mul_f32_e32 v167, v167, v169
	v_mul_f32_e32 v105, v168, v105
	v_lshlrev_b32_e32 v168, 16, v170
	v_and_b32_e32 v169, 0xffff0000, v170
	v_mul_f32_e32 v168, 0xbfb8aa3b, v168
	v_mul_f32_e32 v169, 0xbfb8aa3b, v169
	v_exp_f32_e32 v168, v168
	v_exp_f32_e32 v169, v169
	v_cvt_pk_bf16_f32 v105, v167, v105
	v_cmp_gt_i32_e32 vcc, s88, v142
	v_add_f32_e32 v167, 1.0, v168
	v_add_f32_e32 v168, 1.0, v169
	v_rcp_f32_e32 v167, v167
	v_rcp_f32_e32 v168, v168
	v_lshlrev_b32_e32 v169, 16, v106
	v_and_b32_e32 v106, 0xffff0000, v106
	v_mul_f32_e32 v167, v167, v169
	v_mul_f32_e32 v106, v168, v106
	v_lshlrev_b32_e32 v168, 16, v171
	v_and_b32_e32 v169, 0xffff0000, v171
	v_mul_f32_e32 v168, 0xbfb8aa3b, v168
	v_mul_f32_e32 v169, 0xbfb8aa3b, v169
	v_exp_f32_e32 v168, v168
	v_exp_f32_e32 v169, v169
	v_cvt_pk_bf16_f32 v106, v167, v106
	v_add_f32_e32 v167, 1.0, v168
	v_add_f32_e32 v168, 1.0, v169
	v_rcp_f32_e32 v168, v168
	v_rcp_f32_e32 v167, v167
	v_lshlrev_b32_e32 v169, 16, v107
	v_and_b32_e32 v107, 0xffff0000, v107
	v_mul_f32_e32 v107, v168, v107
	v_mul_f32_e32 v167, v167, v169
	v_cvt_pk_bf16_f32 v107, v167, v107
	s_and_saveexec_b64 s[76:77], vcc
	s_cbranch_execz .LBB0_372
	v_add_u32_e32 v167, s6, v142
	v_cmp_le_i32_e32 vcc, s4, v167
	v_cmp_gt_i32_e64 s[42:43], s5, v167
	s_and_b64 vcc, vcc, s[42:43]
	v_cndmask_b32_e32 v104, 0, v104, vcc
	v_cndmask_b32_e32 v105, 0, v105, vcc
	v_cndmask_b32_e32 v106, 0, v106, vcc
	v_cndmask_b32_e32 v107, 0, v107, vcc
	v_lshl_add_u32 v167, v142, 10, v156
	ds_write_b128 v167, v[104:107]

.LBB0_394:
	s_or_b64 exec, exec, s[76:77]
	v_lshl_add_u32 v26, v108, 1, 0
	s_waitcnt lgkmcnt(0)
	s_barrier
	ds_read_u16 v16, v26
	ds_read_u16 v17, v26 offset:7168
	ds_read_u16 v18, v26 offset:5120
	ds_read_u16 v19, v26 offset:3072
	ds_read_u16 v20, v26 offset:1024
	ds_read_u16 v21, v26 offset:2048
	ds_read_u16 v22, v26 offset:6144
	ds_read_u16 v23, v26 offset:4096
	s_waitcnt lgkmcnt(7)
	v_lshlrev_b32_e32 v48, 16, v16
	s_waitcnt lgkmcnt(3)
	v_lshlrev_b32_e32 v34, 16, v20
	s_waitcnt lgkmcnt(2)
	v_lshlrev_b32_e32 v49, 16, v21
	v_lshlrev_b32_e32 v35, 16, v19
	ds_read_u16 v16, v26 offset:9216
	ds_read_u16 v19, v26 offset:11264
	ds_read_u16 v20, v26 offset:13312
	ds_read_u16 v21, v26 offset:15360
	ds_read_u16 v24, v26 offset:14336
	ds_read_u16 v25, v26 offset:12288
	ds_read_u16 v27, v26 offset:10240
	ds_read_u16 v28, v26 offset:8192
	s_waitcnt lgkmcnt(8)
	v_lshlrev_b32_e32 v50, 16, v23
	v_lshlrev_b32_e32 v36, 16, v18
	v_lshlrev_b32_e32 v51, 16, v22
	v_lshlrev_b32_e32 v37, 16, v17
	s_waitcnt lgkmcnt(0)
	v_lshlrev_b32_e32 v52, 16, v28
	v_lshlrev_b32_e32 v38, 16, v16
	v_lshlrev_b32_e32 v53, 16, v27
	v_lshlrev_b32_e32 v39, 16, v19
	ds_read_u16 v16, v26 offset:17408
	ds_read_u16 v17, v26 offset:19456
	ds_read_u16 v18, v26 offset:21504
	ds_read_u16 v19, v26 offset:23552
	ds_read_u16 v22, v26 offset:22528
	ds_read_u16 v23, v26 offset:20480
	ds_read_u16 v27, v26 offset:18432
	ds_read_u16 v28, v26 offset:16384
	v_lshlrev_b32_e32 v54, 16, v25
	v_lshlrev_b32_e32 v40, 16, v20
	v_lshlrev_b32_e32 v62, 16, v24
	v_lshlrev_b32_e32 v61, 16, v21
	s_waitcnt lgkmcnt(7)
	v_lshlrev_b32_e32 v41, 16, v16
	s_waitcnt lgkmcnt(6)
	v_lshlrev_b32_e32 v42, 16, v17
	ds_read_u16 v16, v26 offset:25600
	ds_read_u16 v17, v26 offset:27648
	ds_read_u16 v20, v26 offset:29696
	ds_read_u16 v21, v26 offset:28672
	ds_read_u16 v24, v26 offset:26624
	ds_read_u16 v25, v26 offset:24576
	s_waitcnt lgkmcnt(7)
	v_lshlrev_b32_e32 v56, 16, v27
	v_lshlrev_b32_e32 v27, 1, v142
	v_readlane_b32 s4, v242, 5
	v_or_b32_e32 v30, 1, v27
	v_lshlrev_b32_e32 v43, 16, v18
	s_waitcnt lgkmcnt(5)
	v_lshlrev_b32_e32 v45, 16, v16
	s_waitcnt lgkmcnt(4)
	v_lshlrev_b32_e32 v46, 16, v17
	v_lshl_add_u32 v16, v141, 2, s4
	v_lshlrev_b32_e32 v17, 12, v142
	v_lshlrev_b32_e32 v18, 11, v30
	v_lshlrev_b32_e32 v55, 16, v28
	v_lshlrev_b32_e32 v57, 16, v23
	v_lshlrev_b32_e32 v58, 16, v22
	v_lshlrev_b32_e32 v44, 16, v19
	s_waitcnt lgkmcnt(0)
	v_lshlrev_b32_e32 v59, 16, v25
	v_lshlrev_b32_e32 v60, 16, v24
	v_lshlrev_b32_e32 v47, 16, v21
	v_lshlrev_b32_e32 v33, 16, v20
	v_add_u32_e32 v28, s82, v27
	v_lshl_add_u32 v29, v108, 2, s4
	s_mov_b32 s42, 0
	s_cmp_eq_u32 s98, 0
	s_cselect_b64 s[76:77], -1, 0
	v_add_u32_e32 v31, v16, v17
	v_add_u32_e32 v32, v16, v18
